# v049 g3 converters on 120 CUs (15360 items per phase), barrier sequence shortened to 67328 items
# speedup vs baseline: 1.0216x; 1.0074x over previous
; DEV void phase_prologue_a(const Frame& F0) {
;     ...
;         constexpr int GU_NB = 2 * FF / 32, GU_ITEMS = 16 * GU_NB;
;         for (int it = F.gw; it < NE * GU_ITEMS; it += F.NGW) { const int e = it / GU_ITEMS, r = it % GU_ITEMS, kb = r / GU_NB, nb = r % GU_NB; const int d0 = 32 * nb, j = d0 >> 8, w = d0 & 255;
;             const float* src = (w < 128 ? GIN(I_WGATE) : GIN(I_WUP)) + ((size_t)l * NE + e) * 1024 * FF;
;             tr_item(src, FF, 128 * j + (w & 127), 64 * kb, (bf16_t*)(F.ws + WS_WGU) + ((size_t)l * NE + e) * 2 * FF * 1024, 1024, d0, scr, F.lane); }
.LBB0_24:
	s_andn2_b64 vcc, exec, s[10:11]
	s_cbranch_vccnz .LBB0_29
	s_lshl_b64 s[20:21], s[2:3], 27
	s_mov_b32 s28, s31
	v_readlane_b32 s100, v255, 51
	s_cmp_lg_u32 s100, 0x100
	s_cbranch_scc1 .Lpro_gu_all
	s_cmp_lg_u32 s14, 0
	s_cbranch_scc1 .LBB0_29
	s_add_i32 s28, s28, 0x7800

; #define WAIT_VM(n) do {} while (0)
; #define LAUNDER_S(x) do {} while (0)
; #define WAIT_VM(n) asm volatile("s_waitcnt vmcnt(" #n ")" ::: "memory")
; #define LAUNDER_S(x) asm volatile("" : "+s"(x))
; DEV int lane_id() { return (int)__builtin_amdgcn_mbcnt_hi(~0u, __builtin_amdgcn_mbcnt_lo(~0u, 0u)); }
; DEV void xcd_barrier(const XcdBarrier& b) {
;     WAIT_VM(0);
;     __syncthreads();
;     int bw = b.wave; LAUNDER_S(bw);
;     if (bw == 0 && lane_id() == 0) {
; DEV void phase_prologue_a(const Frame& F0) {
;     ...
;         constexpr int GU_NB = 2 * FF / 32, GU_ITEMS = 16 * GU_NB;
;         for (int it = F.gw; it < NE * GU_ITEMS; it += F.NGW) { const int e = it / GU_ITEMS, r = it % GU_ITEMS, kb = r / GU_NB, nb = r % GU_NB; const int d0 = 32 * nb, j = d0 >> 8, w = d0 & 255;
.LBB0_115:
	s_or_b64 exec, exec, s[30:31]
	s_cselect_b32 s38, 1, 0
	v_writelane_b32 v255, s38, 61
	v_readlane_b32 s38, v255, 59
	s_add_i32 s39, s38, 1
	v_writelane_b32 v255, s39, 59
	s_mov_b32 s41, 0
	v_readlane_b32 s39, v251, 29
	s_cmp_eq_u32 s39, 0
	s_cbranch_scc1 .Lbw0_none
	v_readlane_b32 s40, v255, 51
	s_cmp_lg_u32 s40, 0x100
	s_cbranch_scc1 .Lbw0_none
	v_readlane_b32 s40, v255, 48
	s_mul_i32 s40, s40, 7
	s_mul_i32 s38, s38, 0x700
	s_add_i32 s40, s40, s38
	s_add_i32 s40, s40, s39
	s_add_i32 s40, s40, -1
	s_cmp_lt_u32 s40, 0x10700
	s_cbranch_scc0 .Lbw0_none
	s_mov_b32 s41, 0
	s_add_i32 s40, s40, 0x3c00
	s_cmp_lt_u32 s40, 0x7800
	s_cbranch_scc1 .Lbw0_have
	s_mov_b32 s41, 1
	s_sub_i32 s40, s40, 0x7800
	s_cmp_lt_u32 s40, 0x4400
	s_cbranch_scc1 .Lbw0_have
	s_mov_b32 s41, 2
	s_sub_i32 s40, s40, 0x4400
	s_cmp_lt_u32 s40, 0x3a00
	s_cbranch_scc1 .Lbw0_have
	s_mov_b32 s41, 3
	s_sub_i32 s40, s40, 0x3a00

; #define WAIT_VM(n) do {} while (0)
; #define LAUNDER_S(x) do {} while (0)
; #define WAIT_VM(n) asm volatile("s_waitcnt vmcnt(" #n ")" ::: "memory")
; #define LAUNDER_S(x) asm volatile("" : "+s"(x))
; DEV int lane_id() { return (int)__builtin_amdgcn_mbcnt_hi(~0u, __builtin_amdgcn_mbcnt_lo(~0u, 0u)); }
; DEV void xcd_barrier(const XcdBarrier& b) {
;     WAIT_VM(0);
;     __syncthreads();
;     int bw = b.wave; LAUNDER_S(bw);
;     if (bw == 0 && lane_id() == 0) {
; DEV void phase_prologue_a(const Frame& F0) {
;     ...
;         constexpr int GU_NB = 2 * FF / 32, GU_ITEMS = 16 * GU_NB;
;         for (int it = F.gw; it < NE * GU_ITEMS; it += F.NGW) { const int e = it / GU_ITEMS, r = it % GU_ITEMS, kb = r / GU_NB, nb = r % GU_NB; const int d0 = 32 * nb, j = d0 >> 8, w = d0 & 255;
.LBB0_241:
	v_writelane_b32 v253, s58, 51
	s_nop 1
	v_writelane_b32 v253, s59, 52
	v_writelane_b32 v253, s56, 53
	s_nop 1
	v_writelane_b32 v253, s57, 54
	s_or_b64 exec, exec, s[34:35]
	s_cselect_b32 s38, 1, 0
	v_writelane_b32 v255, s38, 61
	v_readlane_b32 s38, v255, 59
	s_add_i32 s39, s38, 1
	v_writelane_b32 v255, s39, 59
	s_mov_b32 s41, 0
	v_readlane_b32 s39, v251, 29
	s_cmp_eq_u32 s39, 0
	s_cbranch_scc1 .Lbw2_none
	v_readlane_b32 s40, v255, 51
	s_cmp_lg_u32 s40, 0x100
	s_cbranch_scc1 .Lbw2_none
	v_readlane_b32 s40, v255, 48
	s_mul_i32 s40, s40, 7
	s_mul_i32 s38, s38, 0x700
	s_add_i32 s40, s40, s38
	s_add_i32 s40, s40, s39
	s_add_i32 s40, s40, -1
	s_cmp_lt_u32 s40, 0x10700
	s_cbranch_scc0 .Lbw2_none
	s_mov_b32 s41, 0
	s_add_i32 s40, s40, 0x3c00
	s_cmp_lt_u32 s40, 0x7800
	s_cbranch_scc1 .Lbw2_have
	s_mov_b32 s41, 1
	s_sub_i32 s40, s40, 0x7800
	s_cmp_lt_u32 s40, 0x4400
	s_cbranch_scc1 .Lbw2_have
	s_mov_b32 s41, 2
	s_sub_i32 s40, s40, 0x4400
	s_cmp_lt_u32 s40, 0x3a00
	s_cbranch_scc1 .Lbw2_have
	s_mov_b32 s41, 3
	s_sub_i32 s40, s40, 0x3a00

; #define WAIT_VM(n) do {} while (0)
; #define LAUNDER_S(x) do {} while (0)
; #define WAIT_VM(n) asm volatile("s_waitcnt vmcnt(" #n ")" ::: "memory")
; #define LAUNDER_S(x) asm volatile("" : "+s"(x))
; DEV int lane_id() { return (int)__builtin_amdgcn_mbcnt_hi(~0u, __builtin_amdgcn_mbcnt_lo(~0u, 0u)); }
; DEV void xcd_barrier(const XcdBarrier& b) {
;     WAIT_VM(0);
;     __syncthreads();
;     int bw = b.wave; LAUNDER_S(bw);
;     if (bw == 0 && lane_id() == 0) {
; DEV void phase_prologue_a(const Frame& F0) {
;     ...
;         constexpr int GU_NB = 2 * FF / 32, GU_ITEMS = 16 * GU_NB;
;         for (int it = F.gw; it < NE * GU_ITEMS; it += F.NGW) { const int e = it / GU_ITEMS, r = it % GU_ITEMS, kb = r / GU_NB, nb = r % GU_NB; const int d0 = 32 * nb, j = d0 >> 8, w = d0 & 255;
.LBB0_422:
	s_or_b64 exec, exec, s[34:35]
	s_cselect_b32 s38, 1, 0
	v_writelane_b32 v255, s38, 61
	v_readlane_b32 s38, v255, 59
	s_add_i32 s39, s38, 1
	v_writelane_b32 v255, s39, 59
	s_mov_b32 s41, 0
	v_readlane_b32 s39, v251, 29
	s_cmp_eq_u32 s39, 0
	s_cbranch_scc1 .Lbw3_none
	v_readlane_b32 s40, v255, 51
	s_cmp_lg_u32 s40, 0x100
	s_cbranch_scc1 .Lbw3_none
	v_readlane_b32 s40, v255, 48
	s_mul_i32 s40, s40, 7
	s_mul_i32 s38, s38, 0x700
	s_add_i32 s40, s40, s38
	s_add_i32 s40, s40, s39
	s_add_i32 s40, s40, -1
	s_cmp_lt_u32 s40, 0x10700
	s_cbranch_scc0 .Lbw3_none
	s_mov_b32 s41, 0
	s_add_i32 s40, s40, 0x3c00
	s_cmp_lt_u32 s40, 0x7800
	s_cbranch_scc1 .Lbw3_have
	s_mov_b32 s41, 1
	s_sub_i32 s40, s40, 0x7800
	s_cmp_lt_u32 s40, 0x4400
	s_cbranch_scc1 .Lbw3_have
	s_mov_b32 s41, 2
	s_sub_i32 s40, s40, 0x4400
	s_cmp_lt_u32 s40, 0x3a00
	s_cbranch_scc1 .Lbw3_have
	s_mov_b32 s41, 3
	s_sub_i32 s40, s40, 0x3a00

; #define WAIT_VM(n) do {} while (0)
; #define LAUNDER_S(x) do {} while (0)
; #define WAIT_VM(n) asm volatile("s_waitcnt vmcnt(" #n ")" ::: "memory")
; #define LAUNDER_S(x) asm volatile("" : "+s"(x))
; DEV int lane_id() { return (int)__builtin_amdgcn_mbcnt_hi(~0u, __builtin_amdgcn_mbcnt_lo(~0u, 0u)); }
; DEV void xcd_barrier(const XcdBarrier& b) {
;     WAIT_VM(0);
;     __syncthreads();
;     int bw = b.wave; LAUNDER_S(bw);
;     if (bw == 0 && lane_id() == 0) {
; DEV void phase_prologue_a(const Frame& F0) {
;     ...
;         constexpr int GU_NB = 2 * FF / 32, GU_ITEMS = 16 * GU_NB;
;         for (int it = F.gw; it < NE * GU_ITEMS; it += F.NGW) { const int e = it / GU_ITEMS, r = it % GU_ITEMS, kb = r / GU_NB, nb = r % GU_NB; const int d0 = 32 * nb, j = d0 >> 8, w = d0 & 255;
.Lxb4_join:
.LBB0_811:
	s_or_b64 exec, exec, s[34:35]
	s_cselect_b32 s38, 1, 0
	v_writelane_b32 v255, s38, 61
	v_readlane_b32 s38, v255, 59
	s_add_i32 s39, s38, 1
	v_writelane_b32 v255, s39, 59
	s_mov_b32 s41, 0
	v_readlane_b32 s39, v251, 29
	s_cmp_eq_u32 s39, 0
	s_cbranch_scc1 .Lbw4_none
	v_readlane_b32 s40, v255, 51
	s_cmp_lg_u32 s40, 0x100
	s_cbranch_scc1 .Lbw4_none
	v_readlane_b32 s40, v255, 48
	s_mul_i32 s40, s40, 7
	s_mul_i32 s38, s38, 0x700
	s_add_i32 s40, s40, s38
	s_add_i32 s40, s40, s39
	s_add_i32 s40, s40, -1
	s_cmp_lt_u32 s40, 0x10700
	s_cbranch_scc0 .Lbw4_none
	s_mov_b32 s41, 0
	s_add_i32 s40, s40, 0x3c00
	s_cmp_lt_u32 s40, 0x7800
	s_cbranch_scc1 .Lbw4_have
	s_mov_b32 s41, 1
	s_sub_i32 s40, s40, 0x7800
	s_cmp_lt_u32 s40, 0x4400
	s_cbranch_scc1 .Lbw4_have
	s_mov_b32 s41, 2
	s_sub_i32 s40, s40, 0x4400
	s_cmp_lt_u32 s40, 0x3a00
	s_cbranch_scc1 .Lbw4_have
	s_mov_b32 s41, 3
	s_sub_i32 s40, s40, 0x3a00

; DEV void gemm_g3(const Frame& F0, int l, int vcu) {
;     const Frame F = refresh(F0);
;     pg8::PlainOrder S; S.init((const void*)(F.ws + WS_MERGED), (const bf16_t*)(F.ws + WS_WOUT) + (size_t)l * 1024 * 1024, 1024, (l == DEPTH - 1) ? LATPAD : MPAD, 1024, F.G, vcu);
;     EpiP E; E.O = (bf16_t*)(F.ws + WS_Y); E.ldc = 1024;
;     pg8::gemm_phase(F.lds, 1024, S, E, F.wave, F.lane);
; }
.LBB0_1317:
	v_readlane_b32 s4, v251, 0
	v_readlane_b32 s6, v251, 2
	v_readlane_b32 s7, v251, 3
	s_lshl_b32 s0, s33, 2
	v_readlane_b32 s10, v251, 29
	v_mov_b32_e32 v16, v200
	s_mov_b64 s[2:3], s[6:7]
	s_cmp_ge_i32 s95, s0
	v_readlane_b32 s5, v251, 1
	s_cbranch_scc1 .LBB0_1333
	s_mov_b32 s100, s96
	v_readlane_b32 s101, v253, 62
	s_cmp_gt_u32 s101, 2
	s_cbranch_scc1 .Lg3d_norm
	v_readlane_b32 s101, v255, 51
	s_cmp_lg_u32 s101, 0x100
	s_cbranch_scc1 .Lg3d_norm
	s_movk_i32 s100, 0x88
	v_readlane_b32 s101, v255, 48
	s_cmp_ge_u32 s101, 0x88
	s_cbranch_scc1 .Lsg_entry

; #define WAVE_LDS_SYNC() do { int _z = 0; (void)emu::wave_xchg(&_z, 4); } while (0)
; #define LAS __attribute__((address_space(3)))
; #define WAVE_LDS_SYNC() asm volatile("s_waitcnt lgkmcnt(0)" ::: "memory")
; #define NT_LOAD(p) __builtin_nontemporal_load(p)
; DEV void tr_item(const float* W, int ldw, int col0, int k0, bf16_t* WT, int K, int row0, LAS float* scr, int lane) {
;     ...
;     for (int i = 0; i < 32; ++i) { const int kk = 2 * i + (lane >> 5); scr[kk * 33 + (lane & 31)] = NT_LOAD(&W[(size_t)(k0 + kk) * ldw + col0 + (lane & 31)]); }
;     WAVE_LDS_SYNC();
;     const int c = lane & 7;
; #pragma unroll
;     for (int j = 0; j < 4; ++j) { const int n = (lane >> 3) + 8 * j; const LAS float* s = scr + (8 * c) * 33 + n;
; DEV void phase_prologue_a(const Frame& F0) {
;     ...
;         constexpr int GU_NB = 2 * FF / 32, GU_ITEMS = 16 * GU_NB;
;         for (int it = F.gw; it < NE * GU_ITEMS; it += F.NGW) { const int e = it / GU_ITEMS, r = it % GU_ITEMS, kb = r / GU_NB, nb = r % GU_NB; const int d0 = 32 * nb, j = d0 >> 8, w = d0 & 255;
;             const float* src = (w < 128 ? GIN(I_WGATE) : GIN(I_WUP)) + ((size_t)l * NE + e) * 1024 * FF;
;             tr_item(src, FF, 128 * j + (w & 127), 64 * kb, (bf16_t*)(F.ws + WS_WGU) + ((size_t)l * NE + e) * 2 * FF * 1024, 1024, d0, scr, F.lane); }
.Lsg_entry:
	v_readlane_b32 s36, v253, 62
	s_cmp_gt_u32 s36, 2
	s_cbranch_scc1 .Lsg_done
	v_readlane_b32 s2, v255, 51
	s_cmp_lg_u32 s2, 0x100
	s_cbranch_scc1 .Lsg_done
	v_readlane_b32 s2, v255, 48
	s_cmp_lt_u32 s2, 0x88
	s_cbranch_scc1 .Lsg_done
	v_readlane_b32 s3, v251, 29
	s_sub_i32 s2, s2, 0x88
	s_lshl_b32 s2, s2, 3
	s_add_i32 s2, s2, s3
	v_readlane_b32 s6, v255, 53
	v_readlane_b32 s7, v255, 54
	v_readlane_b32 s4, v255, 55
	v_readlane_b32 s5, v255, 56
	v_readlane_b32 s34, v255, 57
	v_readlane_b32 s35, v255, 58
	s_add_u32 s6, s6, 0x2bc8000
	s_addc_u32 s7, s7, 0
	s_mov_b32 s8, 0
	s_mov_b32 s37, 0
	s_cmp_eq_u32 s36, 0
	s_cbranch_scc1 .Lsg_go
	s_mov_b32 s8, 0x8000000
	s_mov_b32 s37, 0x4400
	s_cmp_eq_u32 s36, 1
	s_cbranch_scc1 .Lsg_go
	s_mov_b32 s8, 0x10000000
	s_mov_b32 s37, 0x3a00
.Lsg_go:
	s_add_u32 s4, s4, s8
	s_addc_u32 s5, s5, 0
	s_add_u32 s34, s34, s8
	s_addc_u32 s35, s35, 0
	s_add_u32 s6, s6, s8
	s_addc_u32 s7, s7, 0
	s_add_i32 s2, s2, s37
	s_add_i32 s101, s37, 0x3c00
	s_lshl_b32 s30, s3, 14
	v_and_b32_e32 v120, 31, v200
	v_lshlrev_b32_e32 v2, 2, v120
	v_lshrrev_b32_e32 v3, 5, v200
	v_and_b32_e32 v4, 7, v200
	v_lshrrev_b32_e32 v6, 3, v200
	v_mul_u32_u24_e32 v7, 33, v3
	v_add_u32_e32 v7, v7, v120
	v_lshl_add_u32 v7, v7, 2, s30
	v_add_u32_e32 v8, 0x400, v7
	v_add_u32_e32 v9, 0x840, v7
	v_add_u32_e32 v10, 0xc40, v7
	v_add_u32_e32 v11, 0x1080, v7
	v_add_u32_e32 v12, 0x1480, v7
	v_add_u32_e32 v13, 0x18c0, v7
	v_add_u32_e32 v14, 0x1cc0, v7
	v_mul_u32_u24_e32 v120, 0x108, v4
	v_add_u32_e32 v120, v120, v6
	v_lshl_add_u32 v15, v120, 2, s30
	v_lshl_add_u32 v122, v3, 13, v2
	v_mov_b32_e32 v123, 0
	v_lshlrev_b32_e32 v124, 4, v4
	v_lshl_add_u32 v124, v6, 11, v124
	v_mov_b32_e32 v125, 0
	s_mov_b64 s[40:41], 0x20000
	s_mov_b64 s[42:43], 0x4000
	s_mov_b64 s[44:45], 0x4000
.Lsg_loop:
	s_lshr_b32 s8, s2, 11
	s_and_b32 s9, s2, 0x7ff
	s_lshr_b32 s10, s9, 7
	s_and_b32 s9, s9, 0x7f
	s_lshl_b32 s24, s10, 19
	s_lshr_b32 s25, s9, 3
	s_lshl_b32 s25, s25, 9
	s_add_i32 s24, s24, s25
	s_and_b32 s25, s9, 3
	s_lshl_b32 s25, s25, 7
	s_add_i32 s24, s24, s25
	s_lshr_b32 s29, s8, 9
	s_lshl_b32 s28, s8, 23
	s_add_u32 s28, s28, s24
	s_addc_u32 s29, s29, 0
	s_bitcmp0_b32 s9, 2
	s_cselect_b32 s24, s4, s34
	s_cselect_b32 s25, s5, s35
	s_add_u32 s28, s28, s24
	s_addc_u32 s29, s29, s25
	s_lshl_b32 s24, s9, 16
	s_lshl_b32 s25, s10, 7
	s_add_i32 s24, s24, s25
	s_lshr_b32 s11, s8, 9
	s_lshl_b32 s10, s8, 23
	s_add_u32 s10, s10, s24
	s_addc_u32 s11, s11, 0
	s_add_u32 s10, s10, s6
	s_addc_u32 s11, s11, s7
	v_lshl_add_u64 v[16:17], s[28:29], 0, v[122:123]
	v_lshl_add_u64 v[18:19], v[16:17], 0, s[44:45]
	v_lshl_add_u64 v[20:21], v[18:19], 0, s[44:45]
	v_lshl_add_u64 v[22:23], v[20:21], 0, s[44:45]
	v_lshl_add_u64 v[24:25], v[22:23], 0, s[44:45]
	v_lshl_add_u64 v[26:27], v[24:25], 0, s[44:45]
	v_lshl_add_u64 v[28:29], v[26:27], 0, s[44:45]
	v_lshl_add_u64 v[30:31], v[28:29], 0, s[44:45]
	global_load_dword v32, v[16:17], off nt
	global_load_dword v33, v[18:19], off nt
	global_load_dword v34, v[20:21], off nt
	global_load_dword v35, v[22:23], off nt
	global_load_dword v36, v[24:25], off nt
	global_load_dword v37, v[26:27], off nt
	global_load_dword v38, v[28:29], off nt
	global_load_dword v39, v[30:31], off nt
	v_lshl_add_u64 v[16:17], v[16:17], 0, s[40:41]
	v_lshl_add_u64 v[18:19], v[18:19], 0, s[40:41]
	v_lshl_add_u64 v[20:21], v[20:21], 0, s[40:41]
	v_lshl_add_u64 v[22:23], v[22:23], 0, s[40:41]
	v_lshl_add_u64 v[24:25], v[24:25], 0, s[40:41]
	v_lshl_add_u64 v[26:27], v[26:27], 0, s[40:41]
	v_lshl_add_u64 v[28:29], v[28:29], 0, s[40:41]
	v_lshl_add_u64 v[30:31], v[30:31], 0, s[40:41]
	global_load_dword v40, v[16:17], off nt
	global_load_dword v41, v[18:19], off nt
	global_load_dword v42, v[20:21], off nt
	global_load_dword v43, v[22:23], off nt
	global_load_dword v44, v[24:25], off nt
	global_load_dword v45, v[26:27], off nt
	global_load_dword v46, v[28:29], off nt
	global_load_dword v47, v[30:31], off nt
	v_lshl_add_u64 v[16:17], v[16:17], 0, s[40:41]
	v_lshl_add_u64 v[18:19], v[18:19], 0, s[40:41]
	v_lshl_add_u64 v[20:21], v[20:21], 0, s[40:41]
	v_lshl_add_u64 v[22:23], v[22:23], 0, s[40:41]
	v_lshl_add_u64 v[24:25], v[24:25], 0, s[40:41]
	v_lshl_add_u64 v[26:27], v[26:27], 0, s[40:41]
	v_lshl_add_u64 v[28:29], v[28:29], 0, s[40:41]
	v_lshl_add_u64 v[30:31], v[30:31], 0, s[40:41]
	global_load_dword v48, v[16:17], off nt
	global_load_dword v49, v[18:19], off nt
	global_load_dword v50, v[20:21], off nt
	global_load_dword v51, v[22:23], off nt
	global_load_dword v52, v[24:25], off nt
	global_load_dword v53, v[26:27], off nt
	global_load_dword v54, v[28:29], off nt
	global_load_dword v55, v[30:31], off nt
	v_lshl_add_u64 v[16:17], v[16:17], 0, s[40:41]
	v_lshl_add_u64 v[18:19], v[18:19], 0, s[40:41]
	v_lshl_add_u64 v[20:21], v[20:21], 0, s[40:41]
	v_lshl_add_u64 v[22:23], v[22:23], 0, s[40:41]
	v_lshl_add_u64 v[24:25], v[24:25], 0, s[40:41]
	v_lshl_add_u64 v[26:27], v[26:27], 0, s[40:41]
	v_lshl_add_u64 v[28:29], v[28:29], 0, s[40:41]
	v_lshl_add_u64 v[30:31], v[30:31], 0, s[40:41]
	global_load_dword v56, v[16:17], off nt
	global_load_dword v57, v[18:19], off nt
	global_load_dword v58, v[20:21], off nt
	global_load_dword v59, v[22:23], off nt
	global_load_dword v60, v[24:25], off nt
	global_load_dword v61, v[26:27], off nt
	global_load_dword v62, v[28:29], off nt
	global_load_dword v63, v[30:31], off nt
	v_lshl_add_u64 v[64:65], s[10:11], 0, v[124:125]
	v_lshl_add_u64 v[66:67], v[64:65], 0, s[42:43]
	v_lshl_add_u64 v[68:69], v[66:67], 0, s[42:43]
	v_lshl_add_u64 v[70:71], v[68:69], 0, s[42:43]
	s_add_i32 s31, s2, 0x3c0
	s_lshr_b32 s8, s31, 11
	s_and_b32 s9, s31, 0x7ff
; #define WAVE_LDS_SYNC() do { int _z = 0; (void)emu::wave_xchg(&_z, 4); } while (0)
; #define LAS __attribute__((address_space(3)))
; #define WAVE_LDS_SYNC() asm volatile("s_waitcnt lgkmcnt(0)" ::: "memory")
; #define NT_LOAD(p) __builtin_nontemporal_load(p)
; DEV void tr_item(const float* W, int ldw, int col0, int k0, bf16_t* WT, int K, int row0, LAS float* scr, int lane) {
; #pragma unroll 8
;     for (int i = 0; i < 32; ++i) { const int kk = 2 * i + (lane >> 5); scr[kk * 33 + (lane & 31)] = NT_LOAD(&W[(size_t)(k0 + kk) * ldw + col0 + (lane & 31)]); }
;     WAVE_LDS_SYNC();
	s_lshr_b32 s10, s9, 7
	s_and_b32 s9, s9, 0x7f
	s_lshl_b32 s24, s10, 19
	s_lshr_b32 s25, s9, 3
	s_lshl_b32 s25, s25, 9
	s_add_i32 s24, s24, s25
	s_and_b32 s25, s9, 3
	s_lshl_b32 s25, s25, 7
	s_add_i32 s24, s24, s25
	s_lshr_b32 s29, s8, 9
	s_lshl_b32 s28, s8, 23
	s_add_u32 s28, s28, s24
	s_addc_u32 s29, s29, 0
	s_bitcmp0_b32 s9, 2
	s_cselect_b32 s24, s4, s34
	s_cselect_b32 s25, s5, s35
	s_add_u32 s28, s28, s24
	s_addc_u32 s29, s29, s25
	s_lshl_b32 s24, s9, 16
	s_lshl_b32 s25, s10, 7
	s_add_i32 s24, s24, s25
	s_lshr_b32 s11, s8, 9
	s_lshl_b32 s10, s8, 23
	s_add_u32 s10, s10, s24
	s_addc_u32 s11, s11, 0
	s_add_u32 s10, s10, s6
	s_addc_u32 s11, s11, s7
	v_lshl_add_u64 v[16:17], s[28:29], 0, v[122:123]
	v_lshl_add_u64 v[18:19], v[16:17], 0, s[44:45]
	v_lshl_add_u64 v[20:21], v[18:19], 0, s[44:45]
	v_lshl_add_u64 v[22:23], v[20:21], 0, s[44:45]
	v_lshl_add_u64 v[24:25], v[22:23], 0, s[44:45]
	v_lshl_add_u64 v[26:27], v[24:25], 0, s[44:45]
	v_lshl_add_u64 v[28:29], v[26:27], 0, s[44:45]
	v_lshl_add_u64 v[30:31], v[28:29], 0, s[44:45]
	global_load_dword v162, v[16:17], off nt
	global_load_dword v163, v[18:19], off nt
	global_load_dword v164, v[20:21], off nt
	global_load_dword v165, v[22:23], off nt
	global_load_dword v166, v[24:25], off nt
	global_load_dword v167, v[26:27], off nt
	global_load_dword v168, v[28:29], off nt
	global_load_dword v169, v[30:31], off nt
	v_lshl_add_u64 v[16:17], v[16:17], 0, s[40:41]
	v_lshl_add_u64 v[18:19], v[18:19], 0, s[40:41]
	v_lshl_add_u64 v[20:21], v[20:21], 0, s[40:41]
	v_lshl_add_u64 v[22:23], v[22:23], 0, s[40:41]
	v_lshl_add_u64 v[24:25], v[24:25], 0, s[40:41]
	v_lshl_add_u64 v[26:27], v[26:27], 0, s[40:41]
	v_lshl_add_u64 v[28:29], v[28:29], 0, s[40:41]
	v_lshl_add_u64 v[30:31], v[30:31], 0, s[40:41]
	global_load_dword v170, v[16:17], off nt
	global_load_dword v171, v[18:19], off nt
	global_load_dword v172, v[20:21], off nt
	global_load_dword v173, v[22:23], off nt
	global_load_dword v174, v[24:25], off nt
	global_load_dword v175, v[26:27], off nt
	global_load_dword v176, v[28:29], off nt
	global_load_dword v177, v[30:31], off nt
	v_lshl_add_u64 v[16:17], v[16:17], 0, s[40:41]
	v_lshl_add_u64 v[18:19], v[18:19], 0, s[40:41]
	v_lshl_add_u64 v[20:21], v[20:21], 0, s[40:41]
	v_lshl_add_u64 v[22:23], v[22:23], 0, s[40:41]
	v_lshl_add_u64 v[24:25], v[24:25], 0, s[40:41]
	v_lshl_add_u64 v[26:27], v[26:27], 0, s[40:41]
	v_lshl_add_u64 v[28:29], v[28:29], 0, s[40:41]
	v_lshl_add_u64 v[30:31], v[30:31], 0, s[40:41]
	global_load_dword v178, v[16:17], off nt
	global_load_dword v179, v[18:19], off nt
	global_load_dword v180, v[20:21], off nt
	global_load_dword v181, v[22:23], off nt
	global_load_dword v182, v[24:25], off nt
	global_load_dword v183, v[26:27], off nt
	global_load_dword v184, v[28:29], off nt
	global_load_dword v185, v[30:31], off nt
	v_lshl_add_u64 v[16:17], v[16:17], 0, s[40:41]
	v_lshl_add_u64 v[18:19], v[18:19], 0, s[40:41]
	v_lshl_add_u64 v[20:21], v[20:21], 0, s[40:41]
	v_lshl_add_u64 v[22:23], v[22:23], 0, s[40:41]
	v_lshl_add_u64 v[24:25], v[24:25], 0, s[40:41]
	v_lshl_add_u64 v[26:27], v[26:27], 0, s[40:41]
	v_lshl_add_u64 v[28:29], v[28:29], 0, s[40:41]
	v_lshl_add_u64 v[30:31], v[30:31], 0, s[40:41]
	global_load_dword v186, v[16:17], off nt
	global_load_dword v187, v[18:19], off nt
	global_load_dword v188, v[20:21], off nt
	global_load_dword v189, v[22:23], off nt
	global_load_dword v190, v[24:25], off nt
	global_load_dword v191, v[26:27], off nt
	global_load_dword v192, v[28:29], off nt
	global_load_dword v193, v[30:31], off nt
	v_lshl_add_u64 v[126:127], s[10:11], 0, v[124:125]
	v_lshl_add_u64 v[128:129], v[126:127], 0, s[42:43]
	v_lshl_add_u64 v[130:131], v[128:129], 0, s[42:43]
	v_lshl_add_u64 v[132:133], v[130:131], 0, s[42:43]
	s_waitcnt vmcnt(62)
	ds_write2_b32 v7, v32, v33 offset1:66
	s_waitcnt vmcnt(60)
	ds_write2_b32 v7, v34, v35 offset0:132 offset1:198
	s_waitcnt vmcnt(58)
	ds_write2_b32 v8, v36, v37 offset0:8 offset1:74
	s_waitcnt vmcnt(56)
	ds_write2_b32 v8, v38, v39 offset0:140 offset1:206
	s_waitcnt vmcnt(54)
	ds_write2_b32 v9, v40, v41 offset1:66
	s_waitcnt vmcnt(52)
	ds_write2_b32 v9, v42, v43 offset0:132 offset1:198
	s_waitcnt vmcnt(50)
	ds_write2_b32 v10, v44, v45 offset0:8 offset1:74
	s_waitcnt vmcnt(48)
	ds_write2_b32 v10, v46, v47 offset0:140 offset1:206
	s_waitcnt vmcnt(46)
	ds_write2_b32 v11, v48, v49 offset1:66
	s_waitcnt vmcnt(44)
	ds_write2_b32 v11, v50, v51 offset0:132 offset1:198
	s_waitcnt vmcnt(42)
	ds_write2_b32 v12, v52, v53 offset0:8 offset1:74
	s_waitcnt vmcnt(40)
	ds_write2_b32 v12, v54, v55 offset0:140 offset1:206
	s_waitcnt vmcnt(38)
	ds_write2_b32 v13, v56, v57 offset1:66
	s_waitcnt vmcnt(36)
; #define WAVE_LDS_SYNC() do { int _z = 0; (void)emu::wave_xchg(&_z, 4); } while (0)
; #define LAS __attribute__((address_space(3)))
; #define WAVE_LDS_SYNC() asm volatile("s_waitcnt lgkmcnt(0)" ::: "memory")
; #define NT_LOAD(p) __builtin_nontemporal_load(p)
; #define NT_STORE(v, p) __builtin_nontemporal_store((v), (p))
; DEV unsigned pk2(float lo, float hi) { return f2bf(lo) | (f2bf(hi) << 16); }
; DEV unsigned pk2(float lo, float hi) { const f32x2n_t v = {lo, hi}; return __builtin_bit_cast(unsigned, __builtin_convertvector(v, bf16x2n_t)); }
; DEV void tr_item(const float* W, int ldw, int col0, int k0, bf16_t* WT, int K, int row0, LAS float* scr, int lane) {
;     ...
;     for (int i = 0; i < 32; ++i) { const int kk = 2 * i + (lane >> 5); scr[kk * 33 + (lane & 31)] = NT_LOAD(&W[(size_t)(k0 + kk) * ldw + col0 + (lane & 31)]); }
;     WAVE_LDS_SYNC();
;     const int c = lane & 7;
; #pragma unroll
;     for (int j = 0; j < 4; ++j) { const int n = (lane >> 3) + 8 * j; const LAS float* s = scr + (8 * c) * 33 + n;
;         u32x4 o; o.x = pk2(s[0 * 33], s[1 * 33]); o.y = pk2(s[2 * 33], s[3 * 33]); o.z = pk2(s[4 * 33], s[5 * 33]); o.w = pk2(s[6 * 33], s[7 * 33]);
;         NT_STORE(o, (u32x4*)(WT + (size_t)(row0 + n) * K + k0 + 8 * c)); }
;     WAVE_LDS_SYNC();
; }
	ds_write2_b32 v13, v58, v59 offset0:132 offset1:198
	s_waitcnt vmcnt(34)
	ds_write2_b32 v14, v60, v61 offset0:8 offset1:74
	s_waitcnt vmcnt(32)
	ds_write2_b32 v14, v62, v63 offset0:140 offset1:206
	ds_read2_b32 v[72:73], v15 offset1:8
	ds_read2_b32 v[74:75], v15 offset0:33 offset1:41
	ds_read2_b32 v[76:77], v15 offset0:66 offset1:74
	ds_read2_b32 v[78:79], v15 offset0:99 offset1:107
	ds_read2_b32 v[80:81], v15 offset0:132 offset1:140
	ds_read2_b32 v[82:83], v15 offset0:165 offset1:173
	ds_read2_b32 v[84:85], v15 offset0:198 offset1:206
	ds_read2_b32 v[86:87], v15 offset0:231 offset1:239
	ds_read2_b32 v[88:89], v15 offset0:16 offset1:24
	ds_read2_b32 v[90:91], v15 offset0:49 offset1:57
	ds_read2_b32 v[92:93], v15 offset0:82 offset1:90
	ds_read2_b32 v[94:95], v15 offset0:115 offset1:123
	s_waitcnt lgkmcnt(4)
	v_cvt_pk_bf16_f32 v104, v72, v74
	v_cvt_pk_bf16_f32 v105, v76, v78
	v_cvt_pk_bf16_f32 v106, v80, v82
	v_cvt_pk_bf16_f32 v107, v84, v86
	v_cvt_pk_bf16_f32 v108, v73, v75
	v_cvt_pk_bf16_f32 v109, v77, v79
	v_cvt_pk_bf16_f32 v110, v81, v83
	v_cvt_pk_bf16_f32 v111, v85, v87
	ds_read2_b32 v[96:97], v15 offset0:148 offset1:156
	ds_read2_b32 v[98:99], v15 offset0:181 offset1:189
	ds_read2_b32 v[100:101], v15 offset0:214 offset1:222
	ds_read2_b32 v[102:103], v15 offset0:247 offset1:255
	global_store_dwordx4 v[64:65], v[104:107], off nt
	global_store_dwordx4 v[66:67], v[108:111], off nt
	s_waitcnt lgkmcnt(0)
	v_cvt_pk_bf16_f32 v112, v88, v90
	v_cvt_pk_bf16_f32 v113, v92, v94
	v_cvt_pk_bf16_f32 v114, v96, v98
	v_cvt_pk_bf16_f32 v115, v100, v102
	v_cvt_pk_bf16_f32 v116, v89, v91
	v_cvt_pk_bf16_f32 v117, v93, v95
	v_cvt_pk_bf16_f32 v118, v97, v99
	v_cvt_pk_bf16_f32 v119, v101, v103
	global_store_dwordx4 v[68:69], v[112:115], off nt
	global_store_dwordx4 v[70:71], v[116:119], off nt
	s_waitcnt vmcnt(34)
	ds_write2_b32 v7, v162, v163 offset1:66
	s_waitcnt vmcnt(32)
	ds_write2_b32 v7, v164, v165 offset0:132 offset1:198
	s_waitcnt vmcnt(30)
	ds_write2_b32 v8, v166, v167 offset0:8 offset1:74
	s_waitcnt vmcnt(28)
	ds_write2_b32 v8, v168, v169 offset0:140 offset1:206
	s_waitcnt vmcnt(26)
	ds_write2_b32 v9, v170, v171 offset1:66
	s_waitcnt vmcnt(24)
	ds_write2_b32 v9, v172, v173 offset0:132 offset1:198
	s_waitcnt vmcnt(22)
	ds_write2_b32 v10, v174, v175 offset0:8 offset1:74
	s_waitcnt vmcnt(20)
	ds_write2_b32 v10, v176, v177 offset0:140 offset1:206
	s_waitcnt vmcnt(18)
	ds_write2_b32 v11, v178, v179 offset1:66
	s_waitcnt vmcnt(16)
	ds_write2_b32 v11, v180, v181 offset0:132 offset1:198
	s_waitcnt vmcnt(14)
	ds_write2_b32 v12, v182, v183 offset0:8 offset1:74
	s_waitcnt vmcnt(12)
	ds_write2_b32 v12, v184, v185 offset0:140 offset1:206
	s_waitcnt vmcnt(10)
	ds_write2_b32 v13, v186, v187 offset1:66
	s_waitcnt vmcnt(8)
	ds_write2_b32 v13, v188, v189 offset0:132 offset1:198
	s_waitcnt vmcnt(6)
	ds_write2_b32 v14, v190, v191 offset0:8 offset1:74
	s_waitcnt vmcnt(4)
	ds_write2_b32 v14, v192, v193 offset0:140 offset1:206
	ds_read2_b32 v[72:73], v15 offset1:8
	ds_read2_b32 v[74:75], v15 offset0:33 offset1:41
	ds_read2_b32 v[76:77], v15 offset0:66 offset1:74
	ds_read2_b32 v[78:79], v15 offset0:99 offset1:107
	ds_read2_b32 v[80:81], v15 offset0:132 offset1:140
	ds_read2_b32 v[82:83], v15 offset0:165 offset1:173
	ds_read2_b32 v[84:85], v15 offset0:198 offset1:206
	ds_read2_b32 v[86:87], v15 offset0:231 offset1:239
	ds_read2_b32 v[88:89], v15 offset0:16 offset1:24
	ds_read2_b32 v[90:91], v15 offset0:49 offset1:57
	ds_read2_b32 v[92:93], v15 offset0:82 offset1:90
	ds_read2_b32 v[94:95], v15 offset0:115 offset1:123
	s_waitcnt lgkmcnt(4)
	v_cvt_pk_bf16_f32 v104, v72, v74
	v_cvt_pk_bf16_f32 v105, v76, v78
	v_cvt_pk_bf16_f32 v106, v80, v82
	v_cvt_pk_bf16_f32 v107, v84, v86
	v_cvt_pk_bf16_f32 v108, v73, v75
	v_cvt_pk_bf16_f32 v109, v77, v79
	v_cvt_pk_bf16_f32 v110, v81, v83
	v_cvt_pk_bf16_f32 v111, v85, v87
	ds_read2_b32 v[96:97], v15 offset0:148 offset1:156
	ds_read2_b32 v[98:99], v15 offset0:181 offset1:189
	ds_read2_b32 v[100:101], v15 offset0:214 offset1:222
	ds_read2_b32 v[102:103], v15 offset0:247 offset1:255
	global_store_dwordx4 v[126:127], v[104:107], off nt
	global_store_dwordx4 v[128:129], v[108:111], off nt
	s_waitcnt lgkmcnt(0)
	v_cvt_pk_bf16_f32 v112, v88, v90
	v_cvt_pk_bf16_f32 v113, v92, v94
	v_cvt_pk_bf16_f32 v114, v96, v98
	v_cvt_pk_bf16_f32 v115, v100, v102
	v_cvt_pk_bf16_f32 v116, v89, v91
	v_cvt_pk_bf16_f32 v117, v93, v95
	v_cvt_pk_bf16_f32 v118, v97, v99
	v_cvt_pk_bf16_f32 v119, v101, v103
	global_store_dwordx4 v[130:131], v[112:115], off nt
	global_store_dwordx4 v[132:133], v[116:119], off nt
	s_add_i32 s2, s2, 0x780
	s_cmp_lt_u32 s2, s101
	s_cbranch_scc1 .Lsg_loop
